# last 192 layer-1 conversion tile units (ffn2 gate tail, ffn2 down) moved into the idle last round of layer 1's first gate/up GEMM; layer 1's first norm phase no longer converts
# baseline (speedup 1.0000x reference)
; __device__ __forceinline__ void convert_layer(PP P, int l, LAS unsigned char* lds, const Ids I) {
;     ...
;     for (int u = BID; u < 7 * 176 + 64; u += NB) {
;         const int mi = u / 176, uu = u - mi * 176;
;         if (mi == 0)      conv_tile4(P->in[I_F1G] + wl, 1024, 2816, (bf16_t*)(ws + WS_WGU1), 5, uu, T, I);
;         else if (mi == 1) conv_tile4(P->in[I_F1U] + wl, 1024, 2816, (bf16_t*)(ws + WS_WGU1), 6, uu, T, I);
;         else if (mi == 2) conv_tile4(P->in[I_F1D] + wl, 2816, 1024, (bf16_t*)(ws + WS_WD1), 0, uu, T, I);
;         else if (mi == 3) conv_tile4(P->in[I_WIN] + wl, 1024, 2816, (bf16_t*)(ws + WS_WIN), 4, uu, T, I);
;         else if (mi == 4) conv_tile4(P->in[I_F2G] + wl, 1024, 2816, (bf16_t*)(ws + WS_WGU2), 5, uu, T, I);
;         else if (mi == 5) conv_tile4(P->in[I_F2U] + wl, 1024, 2816, (bf16_t*)(ws + WS_WGU2), 6, uu, T, I);
;         else if (mi == 6) conv_tile4(P->in[I_F2D] + wl, 2816, 1024, (bf16_t*)(ws + WS_WD2), 0, uu, T, I);
;         else              conv_tile4(P->in[I_WOUT] + (size_t)l * 1024 * 1024, 1024, 1024, (bf16_t*)(ws + WS_WOUT), 0, uu, T, I);
;     }
; __global__ void __launch_bounds__(512) mega(Params Pval) {
;     ...
;             } else if (sub == 1 || sub == 10) {
;                 EpiSwiGLU E{(bf16_t*)(ws + WS_R1)}; run_gemm(lds, (const bf16_t*)(ws + WS_HB), (const bf16_t*)(ws + (sub == 1 ? WS_WGU1 : WS_WGU2)), MT, 2 * FF, 1024, E, I);
.LBB0_412:
	v_readlane_b32 s30, v254, 45
	s_mov_b32 s25, s45
	v_readlane_b32 s27, v254, 47
	s_barrier
	s_cmp_eq_u32 s33, 15
	s_cbranch_scc1 .Lcv_c15
	s_cmp_eq_u32 s33, 12
	s_cbranch_scc0 .LBB0_413
	s_sub_i32 s6, s93, 0xac
	s_cmp_lt_u32 s6, 64
	s_cbranch_scc0 .LBB0_413
	s_mov_b64 s[28:29], s[12:13]
	s_add_i32 s22, s93, 0x424
	s_add_i32 s3, s93, 4
	s_movk_i32 s100, 0x100
	s_mov_b64 s[26:27], 0xb00000
	s_branch .LBB0_504
.Lcv_c15:
	s_cmpk_lt_u32 s93, 0xac
	s_cbranch_scc1 .LBB0_413
	s_mov_b64 s[28:29], s[12:13]
	s_add_i32 s22, s93, 0x364
	s_add_i32 s3, s93, 0xffffff44
	s_movk_i32 s100, 0x54
	s_mov_b64 s[26:27], 0xb00000
	s_branch .LBB0_504

; __global__ void __launch_bounds__(512) mega(Params Pval) {
;     ...
;             if (sub == 0 || sub == 3 || sub == 9) {
;                 if (sub == 0 && l == 1) convert_layer(P, 1, lds, I);
.LBB0_500:
	s_and_b64 vcc, exec, s[0:1]
	s_cbranch_vccz .LBB0_591
	s_cmp_eq_u32 s30, 0
	s_cselect_b64 s[0:1], -1, 0
	s_cmp_eq_u32 s43, 1
	s_cselect_b64 s[4:5], -1, 0
	v_readlane_b32 s8, v254, 16
	s_and_b64 s[6:7], s[0:1], s[4:5]
	v_readlane_b32 s9, v254, 17
	s_and_b64 s[6:7], s[8:9], s[6:7]
	s_andn2_b64 vcc, exec, s[6:7]
	s_mov_b64 s[26:27], 0xb00000
	s_cbranch_vccnz .LBB0_532
	s_branch .LBB0_532
.Lcv_exit:
	s_cmp_eq_u32 s33, 15
	s_cbranch_scc1 .Lcv_ret1
	s_cmp_eq_u32 s33, 12
	s_cbranch_scc1 .Lcv_ret1
	s_branch .Lcv_ret2
